# chunk-prep: K chunk loaded once per head and shared through LDS in MFMA-fragment form (16 fewer 1 KB global loads per wave and unit)
# speedup vs baseline: 1.0088x; 1.0088x over previous
; #define PG8_LAS __attribute__((address_space(3)))
; __device__ __forceinline__ void phase_prep(const Args& a, PG8_LAS unsigned char* lds) {
;     const int tid = threadIdx.x, lane = tid & 63, wave = __builtin_amdgcn_readfirstlane(tid >> 6), half = wave >> 2, lw = wave & 3, q = lane >> 4, r = lane & 15;
;     const int role = (lw - half) & 3;
;     PG8_LAS unsigned char* hb = lds + half * 36864;
;     PG8_LAS float* sG = (PG8_LAS float*)hb; PG8_LAS float* sB = sG + 64; PG8_LAS float* sE = sG + 128; PG8_LAS float* sK = sG + 192; PG8_LAS float* sL = sG + 256;
;     PG8_LAS unsigned char* Tu = hb + 17408; PG8_LAS unsigned char* Tw = Tu + 9216;
;     const bf16_t* qb = (const bf16_t*)(a.ws + WS_QB); const bf16_t* kb = (const bf16_t*)(a.ws + WS_KB);
;     const bf16_t* kT = (const bf16_t*)(a.ws + WS_KT); const bf16_t* vT = (const bf16_t*)(a.ws + WS_VT);
;     const float* betaB = (const float*)(a.ws + WS_BETA); const float* gB = (const float*)(a.ws + WS_G); float* glast = (float*)(a.ws + WS_GL);
;     for (int unit = blockIdx.x; unit < 1024; unit += gridDim.x) {
;         const int hp = unit & 1, bn = unit >> 1, h = 2 * hp + half, item = bn * 4 + h; const size_t r0 = (size_t)bn * 64;
;         unsigned char* pi = a.ws + WS_PREP + (size_t)item * PREP_ITEM;
;         bf16_t* wp = (bf16_t*)(pi + PI_W); bf16_t* qgp = (bf16_t*)(pi + PI_QG); bf16_t* kdTp = (bf16_t*)(pi + PI_KD); bf16_t* uT = (bf16_t*)(pi + PI_UT); bf16_t* aqkp = (bf16_t*)(pi + PI_AQ);
;         const bf16_t* qbase = qb + r0 * 512 + h * 128; const bf16_t* kbase = kb + r0 * 512 + h * 128;
;         const bf16_t* kTb = kT + ((size_t)bn * 512 + h * 128) * 64; const bf16_t* vTb = vT + ((size_t)bn * 512 + h * 128) * 64;
;         bf16x8 ak[4], aq[4], bkf[2][4];
;     ...
;             for (int i = 0; i < 64; ++i) x[i] = (i == lane) ? 1.0f : 0.0f;
.LBB0_249:
	s_or_b64 exec, exec, s[0:1]
	s_add_u32 s10, s16, 0x2000000
	s_addc_u32 s11, s17, 0
	v_readlane_b32 s0, v253, 17
	s_bitcmp0_b32 s0, 3
	s_waitcnt lgkmcnt(0)
	s_barrier
	s_cbranch_scc1 .LBB0_301
	s_cmpk_gt_i32 s82, 0x3ff
	v_readfirstlane_b32 s0, v152
	v_and_b32_e32 v254, 63, v152
	v_lshlrev_b32_e32 v254, 4, v254
	v_lshrrev_b32_e32 v255, 8, v152
	v_mul_u32_u24_e32 v255, 0x6200, v255
	v_add_u32_e32 v254, v254, v255
	v_add_u32_e32 v254, 0x1a000, v254
	v_bfe_u32 v255, v152, 6, 2
	v_lshl_add_u32 v255, v255, 12, v254
	s_cbranch_scc1 .LBB0_301
	v_mbcnt_lo_u32_b32 v0, -1, 0
	s_waitcnt vmcnt(14)
	v_mbcnt_hi_u32_b32 v7, -1, v0
	s_waitcnt vmcnt(12)
	v_and_b32_e32 v9, 64, v7
	s_waitcnt vmcnt(7)
	v_add_u32_e32 v16, -1, v7
	v_cmp_lt_i32_e32 vcc, v16, v9
	v_and_b32_e32 v1, 63, v152
	v_bfrev_b32_e32 v0, 0.5
	v_cndmask_b32_e32 v16, v16, v7, vcc
	v_lshlrev_b32_e32 v131, 2, v16
	v_add_u32_e32 v16, -2, v7
	v_cmp_lt_i32_e32 vcc, v16, v9
	v_lshl_or_b32 v99, v7, 2, v0
	s_lshr_b32 s1, s0, 6
	v_cndmask_b32_e32 v16, v16, v7, vcc
	v_lshlrev_b32_e32 v132, 2, v16
	v_add_u32_e32 v16, -4, v7
	v_cmp_lt_i32_e32 vcc, v16, v9
	s_lshr_b32 s33, s0, 8
	v_writelane_b32 v253, s76, 39
	v_cndmask_b32_e32 v16, v16, v7, vcc
	v_lshlrev_b32_e32 v133, 2, v16
	v_add_u32_e32 v16, -8, v7
	v_cmp_lt_i32_e32 vcc, v16, v9
	s_sub_i32 s1, s1, s33
	v_writelane_b32 v253, s77, 40
	v_cndmask_b32_e32 v16, v16, v7, vcc
	v_lshlrev_b32_e32 v134, 2, v16
	v_add_u32_e32 v16, -16, v7
	v_cmp_lt_i32_e32 vcc, v16, v9
	s_and_b32 s28, s1, 3
	s_mul_i32 s1, s33, 0x9000
	v_cndmask_b32_e32 v16, v16, v7, vcc
	v_lshlrev_b32_e32 v135, 2, v16
	v_subrev_u32_e32 v16, 32, v7
	v_cmp_lt_i32_e32 vcc, v16, v9
	v_writelane_b32 v253, s78, 41
	s_add_i32 s4, s1, 0
	v_cndmask_b32_e32 v7, v16, v7, vcc
	v_cmp_eq_u32_e32 vcc, 1, v1
	v_writelane_b32 v253, s79, 42
	s_add_u32 s1, s16, 0x10000000
	v_cndmask_b32_e64 v140, 0, 1.0, vcc
	v_cmp_eq_u32_e32 vcc, 2, v1
	v_writelane_b32 v253, s1, 43
	s_addc_u32 s1, s17, 0
	v_cndmask_b32_e64 v141, 0, 1.0, vcc
	v_cmp_eq_u32_e32 vcc, 3, v1
	v_writelane_b32 v253, s1, 44
	s_add_u32 s1, s16, 0x12000000
	v_cndmask_b32_e64 v142, 0, 1.0, vcc
	v_cmp_eq_u32_e32 vcc, 4, v1
	v_writelane_b32 v253, s1, 45
	s_addc_u32 s1, s17, 0
	v_cndmask_b32_e64 v143, 0, 1.0, vcc
	v_cmp_eq_u32_e32 vcc, 5, v1
	v_writelane_b32 v253, s1, 46
	s_add_u32 s1, s16, 0x4000000
	v_cndmask_b32_e64 v144, 0, 1.0, vcc
	v_cmp_eq_u32_e32 vcc, 6, v1
	v_writelane_b32 v253, s1, 47
	s_addc_u32 s1, s17, 0
	v_cndmask_b32_e64 v145, 0, 1.0, vcc
	v_cmp_eq_u32_e32 vcc, 7, v1
	s_add_u32 s6, s16, 0x1800000
	s_addc_u32 s7, s17, 0
	v_cndmask_b32_e64 v146, 0, 1.0, vcc
	v_cmp_eq_u32_e32 vcc, 8, v1
	v_writelane_b32 v253, s1, 48
	s_add_u32 s8, s16, 0x1880000
	v_cndmask_b32_e64 v147, 0, 1.0, vcc
	v_cmp_eq_u32_e32 vcc, 9, v1
	v_writelane_b32 v253, s6, 49
	s_addc_u32 s9, s17, 0
	v_cndmask_b32_e64 v148, 0, 1.0, vcc
	v_cmp_eq_u32_e32 vcc, 10, v1
	v_writelane_b32 v253, s7, 50
	s_add_u32 s1, s16, 0x1b00000
	v_cndmask_b32_e64 v149, 0, 1.0, vcc
	v_cmp_eq_u32_e32 vcc, 11, v1
	v_writelane_b32 v253, s1, 51
	s_addc_u32 s1, s17, 0
	v_cndmask_b32_e64 v150, 0, 1.0, vcc
	v_cmp_eq_u32_e32 vcc, 12, v1
	s_bfe_u32 s0, s0, 0x20006
	s_cmp_lg_u32 s28, 0
	v_cndmask_b32_e64 v151, 0, 1.0, vcc
	v_cmp_eq_u32_e32 vcc, 13, v1
	v_writelane_b32 v253, s1, 52
	s_cselect_b64 s[6:7], -1, 0
	v_cndmask_b32_e64 v154, 0, 1.0, vcc
	v_cmp_eq_u32_e32 vcc, 14, v1
	v_writelane_b32 v253, s6, 53
	s_cmp_eq_u32 s0, 0
	v_cndmask_b32_e64 v155, 0, 1.0, vcc
	v_cmp_eq_u32_e32 vcc, 15, v1
	v_writelane_b32 v253, s7, 54
	s_cselect_b64 s[6:7], -1, 0
	v_cndmask_b32_e64 v156, 0, 1.0, vcc
	v_cmp_eq_u32_e32 vcc, 16, v1
	v_mov_b32_e32 v97, 0
	v_writelane_b32 v253, s6, 55
	v_cndmask_b32_e64 v157, 0, 1.0, vcc
	v_cmp_eq_u32_e32 vcc, 17, v1
	v_and_b32_e32 v3, 15, v152
	v_bfe_u32 v5, v152, 4, 2
	v_cndmask_b32_e64 v158, 0, 1.0, vcc
	v_cmp_eq_u32_e32 vcc, 18, v1
	v_writelane_b32 v253, s7, 56
	v_cmp_eq_u32_sdwa s[6:7], v152, v97 src0_sel:BYTE_0 src1_sel:DWORD
	v_cndmask_b32_e64 v159, 0, 1.0, vcc
	v_cmp_eq_u32_e32 vcc, 19, v1
	v_lshlrev_b32_e32 v11, 1, v152
	v_and_b32_e32 v0, 3, v152
	v_cndmask_b32_e64 v160, 0, 1.0, vcc
	v_cmp_eq_u32_e32 vcc, 20, v1
	s_lshl_b32 s1, s0, 6
	v_lshlrev_b32_e32 v6, 9, v3
	v_cndmask_b32_e64 v161, 0, 1.0, vcc
	v_cmp_eq_u32_e32 vcc, 21, v1
	v_lshlrev_b32_e32 v12, 3, v5
	v_writelane_b32 v253, s6, 57
	v_cndmask_b32_e64 v162, 0, 1.0, vcc
	v_cmp_eq_u32_e32 vcc, 22, v1
	v_and_or_b32 v13, v11, 24, v0
	v_lshlrev_b32_e32 v0, 2, v5
	v_cndmask_b32_e64 v163, 0, 1.0, vcc
	v_cmp_eq_u32_e32 vcc, 23, v1
	s_add_i32 s1, s4, s1
	v_and_b32_e32 v2, 48, v152
	v_cndmask_b32_e64 v164, 0, 1.0, vcc
	v_cmp_eq_u32_e32 vcc, 24, v1
	v_lshl_or_b32 v4, s28, 6, v1
	v_lshlrev_b32_e32 v10, 6, v3
	v_cndmask_b32_e64 v165, 0, 1.0, vcc
	v_cmp_eq_u32_e32 vcc, 25, v1
	v_lshl_or_b32 v8, s0, 13, v6
	v_writelane_b32 v253, s7, 58
	v_cndmask_b32_e64 v166, 0, 1.0, vcc
	v_cmp_eq_u32_e32 vcc, 26, v1
	v_lshl_or_b32 v33, s0, 4, v0
	v_add_u32_e32 v15, s1, v2
	v_add_u32_e32 v96, 0xffffff80, v4
	v_lshl_or_b32 v4, s0, 5, v12
	v_lshl_or_b32 v10, s0, 11, v10
	v_cmp_gt_u32_e64 s[0:1], 2, v1
	v_cndmask_b32_e64 v167, 0, 1.0, vcc
	v_cmp_eq_u32_e32 vcc, 27, v1
	v_writelane_b32 v253, s0, 59
	v_or_b32_e32 v35, 1, v33
	v_cndmask_b32_e64 v168, 0, 1.0, vcc
	v_cmp_eq_u32_e32 vcc, 28, v1
	v_writelane_b32 v253, s1, 60
	v_cmp_gt_u32_e64 s[0:1], 4, v1
	v_cndmask_b32_e64 v169, 0, 1.0, vcc
	v_cmp_eq_u32_e32 vcc, 29, v1
	v_writelane_b32 v253, s0, 61
	v_or_b32_e32 v37, 2, v33
	v_cndmask_b32_e64 v170, 0, 1.0, vcc
	v_cmp_eq_u32_e32 vcc, 30, v1
	v_writelane_b32 v253, s1, 62
	v_cmp_gt_u32_e64 s[0:1], 8, v1
	v_cndmask_b32_e64 v171, 0, 1.0, vcc
	v_cmp_eq_u32_e32 vcc, 31, v1
	v_writelane_b32 v253, s0, 63
	v_or_b32_e32 v39, 3, v33
	v_cndmask_b32_e64 v172, 0, 1.0, vcc
	v_cmp_eq_u32_e32 vcc, 32, v1
	v_writelane_b32 v252, s1, 0
	v_cmp_gt_u32_e64 s[0:1], 16, v1
	v_cndmask_b32_e64 v173, 0, 1.0, vcc
	v_cmp_eq_u32_e32 vcc, 33, v1
	v_writelane_b32 v252, s0, 1
	v_or_b32_e32 v25, 16, v3
	v_cndmask_b32_e64 v174, 0, 1.0, vcc
	v_cmp_eq_u32_e32 vcc, 34, v1
	v_writelane_b32 v252, s1, 2
	v_cmp_gt_u32_e64 s[0:1], 32, v1
	v_cndmask_b32_e64 v175, 0, 1.0, vcc
	v_cmp_eq_u32_e32 vcc, 35, v1
	v_writelane_b32 v252, s0, 3
	v_lshlrev_b32_e32 v136, 2, v7
	v_cndmask_b32_e64 v176, 0, 1.0, vcc
	v_cmp_eq_u32_e32 vcc, 36, v1
	v_writelane_b32 v252, s1, 4
	v_cmp_ge_u32_e64 s[0:1], v33, v3
	v_cndmask_b32_e64 v177, 0, 1.0, vcc
	v_cmp_eq_u32_e32 vcc, 37, v1
	v_writelane_b32 v252, s0, 5
	v_lshlrev_b32_e32 v7, 6, v33
	v_cndmask_b32_e64 v178, 0, 1.0, vcc
	v_cmp_eq_u32_e32 vcc, 38, v1
	v_writelane_b32 v252, s1, 6
	v_cmp_gt_u32_e64 s[0:1], v33, v3
	v_cndmask_b32_e64 v179, 0, 1.0, vcc
	v_cmp_eq_u32_e32 vcc, 39, v1
	v_writelane_b32 v252, s0, 7
	v_lshlrev_b32_e32 v9, 6, v35
	v_cndmask_b32_e64 v180, 0, 1.0, vcc
	v_cmp_eq_u32_e32 vcc, 40, v1
	v_writelane_b32 v252, s1, 8
	v_cmp_lt_u32_e64 s[0:1], v35, v3
	v_cndmask_b32_e64 v181, 0, 1.0, vcc
	v_cmp_eq_u32_e32 vcc, 41, v1
	v_writelane_b32 v252, s0, 9
	s_waitcnt vmcnt(4)
; __device__ __forceinline__ void phase_prep(const Args& a, PG8_LAS unsigned char* lds) {
;     ...
;         const int hp = unit & 1, bn = unit >> 1, h = 2 * hp + half, item = bn * 4 + h; const size_t r0 = (size_t)bn * 64;
;         unsigned char* pi = a.ws + WS_PREP + (size_t)item * PREP_ITEM;
;         bf16_t* wp = (bf16_t*)(pi + PI_W); bf16_t* qgp = (bf16_t*)(pi + PI_QG); bf16_t* kdTp = (bf16_t*)(pi + PI_KD); bf16_t* uT = (bf16_t*)(pi + PI_UT); bf16_t* aqkp = (bf16_t*)(pi + PI_AQ);
;         const bf16_t* qbase = qb + r0 * 512 + h * 128; const bf16_t* kbase = kb + r0 * 512 + h * 128;
;         const bf16_t* kTb = kT + ((size_t)bn * 512 + h * 128) * 64; const bf16_t* vTb = vT + ((size_t)bn * 512 + h * 128) * 64;
;         bf16x8 ak[4], aq[4], bkf[2][4];
; #pragma unroll
;         for (int s = 0; s < 4; ++s) { ak[s] = *(const bf16x8*)(kbase + (size_t)(16 * lw + r) * 512 + 32 * s + 8 * q); aq[s] = *(const bf16x8*)(qbase + (size_t)(16 * lw + r) * 512 + 32 * s + 8 * q); }
; #pragma unroll
;         for (int tj = 0; tj < 2; ++tj)
; #pragma unroll
;             for (int s = 0; s < 4; ++s) bkf[tj][s] = *(const bf16x8*)(kbase + (size_t)(16 * tj + r) * 512 + 32 * s + 8 * q);
;         bf16x8 pv[2][2], pk[2][2];
;         if (role != 0) {
; #pragma unroll
;         for (int cc = 0; cc < 2; ++cc) { const int ct = 2 * lw + cc;
;             pv[cc][0] = *(const bf16x8*)(vTb + (size_t)(16 * ct + r) * 64 + 8 * q); pv[cc][1] = *(const bf16x8*)(vTb + (size_t)(16 * ct + r) * 64 + 32 + 8 * q);
;             pk[cc][0] = *(const bf16x8*)(kTb + (size_t)(16 * ct + r) * 64 + 8 * q); pk[cc][1] = *(const bf16x8*)(kTb + (size_t)(16 * ct + r) * 64 + 32 + 8 * q); } }
;         float gv = gB[(r0 + lane) * 4 + h];
; #pragma unroll
;         for (int off = 1; off < 64; off <<= 1) { const float t = __shfl_up(gv, off); if (lane >= off) gv += t; }
;         const float g63 = __shfl(gv, 63);
;         if (lw == 0) { sG[lane] = gv; sB[lane] = betaB[(r0 + lane) * 4 + h]; sE[lane] = __expf(gv); sK[lane] = __expf(g63 - gv); }
;         if ((tid & 255) == 0) glast[item] = __expf(g63);
;         __syncthreads();
;         {
; #pragma unroll
;             for (int tj = 0; tj < 4; ++tj) {
;                 f32x4 ckk = {0.f, 0.f, 0.f, 0.f}, cqk = {0.f, 0.f, 0.f, 0.f};
; #pragma unroll
	v_lshlrev_b32_e32 v19, 6, v37
	v_cndmask_b32_e64 v182, 0, 1.0, vcc
	v_cmp_eq_u32_e32 vcc, 42, v1
	v_writelane_b32 v252, s1, 10
	v_cmp_ge_u32_e64 s[0:1], v35, v3
	v_cndmask_b32_e64 v183, 0, 1.0, vcc
	v_cmp_eq_u32_e32 vcc, 43, v1
	v_writelane_b32 v252, s0, 11
	s_waitcnt vmcnt(2)
	v_lshlrev_b32_e32 v21, 6, v39
	v_cndmask_b32_e64 v184, 0, 1.0, vcc
	v_cmp_eq_u32_e32 vcc, 44, v1
	v_writelane_b32 v252, s1, 12
	v_cmp_lt_u32_e64 s[0:1], v37, v3
	v_cndmask_b32_e64 v185, 0, 1.0, vcc
	v_cmp_eq_u32_e32 vcc, 45, v1
	v_writelane_b32 v252, s0, 13
	v_or_b32_e32 v27, 4, v13
	v_cndmask_b32_e64 v186, 0, 1.0, vcc
	v_cmp_eq_u32_e32 vcc, 46, v1
	v_writelane_b32 v252, s1, 14
	v_cmp_ge_u32_e64 s[0:1], v37, v3
	v_cndmask_b32_e64 v187, 0, 1.0, vcc
	v_cmp_eq_u32_e32 vcc, 47, v1
	v_writelane_b32 v252, s0, 15
	v_or_b32_e32 v16, v7, v13
	v_cndmask_b32_e64 v188, 0, 1.0, vcc
	v_cmp_eq_u32_e32 vcc, 48, v1
	v_writelane_b32 v252, s1, 16
	v_cmp_gt_u32_e64 s[0:1], v37, v3
	v_cndmask_b32_e64 v189, 0, 1.0, vcc
	v_cmp_eq_u32_e32 vcc, 49, v1
	v_writelane_b32 v252, s0, 17
	v_or_b32_e32 v18, v9, v13
	v_cndmask_b32_e64 v190, 0, 1.0, vcc
	v_cmp_eq_u32_e32 vcc, 50, v1
	v_writelane_b32 v252, s1, 18
	v_cmp_lt_u32_e64 s[0:1], v39, v3
	v_cndmask_b32_e64 v191, 0, 1.0, vcc
	v_cmp_eq_u32_e32 vcc, 51, v1
	v_writelane_b32 v252, s0, 19
	v_or_b32_e32 v20, v19, v13
	v_cndmask_b32_e64 v192, 0, 1.0, vcc
	v_cmp_eq_u32_e32 vcc, 52, v1
	v_writelane_b32 v252, s1, 20
	v_cmp_ge_u32_e64 s[0:1], v39, v3
	v_cndmask_b32_e64 v193, 0, 1.0, vcc
	v_cmp_eq_u32_e32 vcc, 53, v1
	v_writelane_b32 v252, s0, 21
	v_or_b32_e32 v22, v21, v13
	v_cndmask_b32_e64 v194, 0, 1.0, vcc
	v_cmp_eq_u32_e32 vcc, 54, v1
	v_writelane_b32 v252, s1, 22
	v_cmp_gt_u32_e64 s[0:1], v39, v3
	v_cndmask_b32_e64 v195, 0, 1.0, vcc
	v_cmp_eq_u32_e32 vcc, 55, v1
	v_writelane_b32 v252, s0, 23
	v_or_b32_e32 v24, v7, v27
	v_cndmask_b32_e64 v196, 0, 1.0, vcc
	v_cmp_eq_u32_e32 vcc, 56, v1
	v_writelane_b32 v252, s1, 24
	v_cmp_ge_u32_e64 s[0:1], v33, v25
	v_cndmask_b32_e64 v197, 0, 1.0, vcc
	v_cmp_eq_u32_e32 vcc, 57, v1
	v_writelane_b32 v252, s0, 25
	v_or_b32_e32 v26, v9, v27
	v_or_b32_e32 v28, v19, v27
	v_or_b32_e32 v30, v21, v27
	v_or_b32_e32 v27, 32, v13
	v_or_b32_e32 v13, 36, v13
	v_cndmask_b32_e64 v198, 0, 1.0, vcc
	v_cmp_eq_u32_e32 vcc, 58, v1
	v_add_u32_e32 v17, s4, v2
	v_lshlrev_b32_e32 v2, 7, v3
	v_lshl_add_u32 v137, v3, 2, s4
	v_cmp_lt_u32_e64 s[12:13], v33, v3
	v_lshlrev_b32_e32 v23, 8, v3
	v_writelane_b32 v252, s1, 26
	v_cmp_gt_u32_e64 s[0:1], v33, v25
	v_or_b32_e32 v41, 32, v3
	v_or_b32_e32 v34, v9, v27
	v_or_b32_e32 v43, 48, v3
	v_or_b32_e32 v42, v9, v13
	v_cndmask_b32_e64 v199, 0, 1.0, vcc
	v_cmp_eq_u32_e32 vcc, 59, v1
	v_mul_u32_u24_e32 v9, 0x90, v3
	v_lshlrev_b32_e32 v3, 4, v3
	v_writelane_b32 v252, s0, 27
	v_cndmask_b32_e64 v200, 0, 1.0, vcc
	v_cmp_eq_u32_e32 vcc, 60, v1
	v_lshl_or_b32 v102, v5, 10, v3
	v_add_u32_e32 v3, s4, v0
	v_writelane_b32 v252, s1, 28
	v_cmp_lt_u32_e64 s[0:1], v35, v25
	v_cndmask_b32_e64 v201, 0, 1.0, vcc
	v_cmp_eq_u32_e32 vcc, 61, v1
	v_add_u32_e32 v206, 0x200, v3
	v_lshlrev_b32_e32 v3, 4, v152
	v_writelane_b32 v252, s0, 29
	v_cndmask_b32_e64 v202, 0, 1.0, vcc
	v_cmp_eq_u32_e32 vcc, 62, v1
	s_add_u32 s29, s16, 0x16000000
	v_and_b32_e32 v3, 0xc0, v3
	v_lshlrev_b32_e32 v98, 2, v1
	v_writelane_b32 v252, s1, 30
	v_cmp_eq_u32_e64 s[62:63], 0, v1
	v_cndmask_b32_e64 v203, 0, 1.0, vcc
	v_cmp_eq_u32_e32 vcc, 63, v1
	v_lshl_add_u32 v205, v1, 1, s4
	v_or_b32_e32 v1, 0x1f80, v11
	s_addc_u32 s30, s17, 0
	s_lshl_b32 s0, s33, 7
	v_lshl_or_b32 v3, v5, 8, v3
	v_and_b32_e32 v5, 1, v152
	v_lshlrev_b32_e32 v11, 2, v152
	v_writelane_b32 v252, s0, 31
	v_lshlrev_b32_e32 v5, 5, v5
	v_and_b32_e32 v11, 8, v11
	v_lshlrev_b64 v[100:101], 7, v[96:97]
	v_lshlrev_b32_e32 v14, 6, v96
	v_cmp_lt_u32_e64 s[36:37], v33, v25
	v_cmp_ge_u32_e64 s[44:45], v35, v25
	v_cmp_lt_u32_e64 s[46:47], v37, v25
	v_cmp_ge_u32_e64 s[48:49], v37, v25
	v_cmp_gt_u32_e64 s[50:51], v37, v25
	v_cmp_lt_u32_e64 s[52:53], v39, v25
	v_cmp_ge_u32_e64 s[54:55], v39, v25
	v_cmp_gt_u32_e64 s[56:57], v39, v25
	v_lshlrev_b32_e32 v25, 8, v25
	v_or_b32_e32 v32, v7, v27
	v_or_b32_e32 v36, v19, v27
	v_or_b32_e32 v38, v21, v27
	v_lshlrev_b32_e32 v27, 8, v41
	v_or_b32_e32 v40, v7, v13
	v_or_b32_e32 v44, v19, v13
	v_or_b32_e32 v46, v21, v13
	v_lshlrev_b32_e32 v7, 8, v43
	v_or_b32_e32 v48, 0x800, v2
	v_or_b32_e32 v50, 0x1000, v2
	v_or_b32_e32 v52, 0x1800, v2
	v_or3_b32 v96, v3, v5, v11
	s_mov_b64 s[0:1], 0x16004800
	v_writelane_b32 v252, s4, 32
	s_mov_b32 s15, 0
	v_add_u32_e32 v130, s4, v98
	v_lshl_add_u32 v138, v33, 2, s4
	v_cmp_lt_u32_e64 s[58:59], v33, v41
	v_cmp_ge_u32_e64 s[60:61], v33, v41
	v_cndmask_b32_e64 v139, 0, 1.0, s[62:63]
	v_cndmask_b32_e64 v204, 0, 1.0, vcc
	v_mov_b32_e32 v103, v97
	s_lshl_b32 s31, s82, 3
	s_mov_b64 s[74:75], s[80:81]
	s_mov_b32 s34, 2
	v_lshl_add_u64 v[104:105], v[96:97], 0, s[0:1]
	v_lshlrev_b32_e32 v106, 1, v8
	v_lshlrev_b32_e32 v96, 1, v12
	v_lshlrev_b32_e32 v108, 1, v6
	v_lshlrev_b32_e32 v207, 1, v16
	v_lshlrev_b32_e32 v208, 1, v18
	v_lshlrev_b32_e32 v209, 1, v20
	v_lshlrev_b32_e32 v210, 1, v22
	v_add_u32_e32 v211, v15, v23
	v_lshlrev_b32_e32 v212, 1, v24
	v_lshlrev_b32_e32 v213, 1, v26
	v_lshlrev_b32_e32 v214, 1, v28
	v_lshlrev_b32_e32 v215, 1, v30
	v_add_u32_e32 v216, v15, v25
	v_lshlrev_b32_e32 v217, 1, v32
	v_lshlrev_b32_e32 v218, 1, v34
	v_lshlrev_b32_e32 v219, 1, v36
	v_lshlrev_b32_e32 v220, 1, v38
	v_add_u32_e32 v221, v15, v27
	s_mov_b32 s35, 0xc000
	v_lshlrev_b32_e32 v222, 1, v40
	v_lshlrev_b32_e32 v223, 1, v42
	v_lshlrev_b32_e32 v224, 1, v44
	v_lshlrev_b32_e32 v225, 1, v46
	v_add_u32_e32 v226, v15, v7
	v_lshlrev_b32_e32 v110, 1, v14
	v_add_u32_e32 v227, s4, v1
	v_add_u32_e32 v228, v17, v9
	v_lshlrev_b32_e32 v112, 1, v0
	v_lshlrev_b32_e32 v114, 1, v10
	v_lshlrev_b32_e32 v116, 1, v4
	v_lshlrev_b32_e32 v118, 1, v2
	v_lshlrev_b32_e32 v120, 1, v48
	v_lshlrev_b32_e32 v122, 1, v50
	v_lshlrev_b32_e32 v124, 1, v52
	v_mov_b32_e32 v229, 0x12000
	v_writelane_b32 v252, s82, 33
	s_lshl_b32 s38, s82, 2
	s_add_i32 s98, s38, 4
	v_cmp_gt_u32_e64 s[64:65], v33, v41
	v_cmp_lt_u32_e64 s[66:67], v35, v41
	v_cmp_ge_u32_e64 s[68:69], v35, v41
	v_cmp_lt_u32_e64 s[70:71], v37, v41
	v_cmp_ge_u32_e64 s[72:73], v37, v41
	v_cmp_gt_u32_e64 s[42:43], v37, v41
	v_cmp_lt_u32_e64 s[76:77], v39, v41
	v_cmp_ge_u32_e64 s[78:79], v39, v41
	v_cmp_gt_u32_e64 s[80:81], v39, v41
	v_cmp_lt_u32_e64 s[82:83], v33, v43
	v_cmp_ge_u32_e64 s[84:85], v33, v43
	v_cmp_gt_u32_e64 s[86:87], v33, v43
	v_cmp_lt_u32_e64 s[88:89], v35, v43
	v_cmp_ge_u32_e64 s[90:91], v35, v43
	v_cmp_lt_u32_e64 s[92:93], v37, v43
	v_cmp_ge_u32_e64 s[94:95], v37, v43
	v_cmp_gt_u32_e64 s[96:97], v37, v43
	v_cmp_lt_u32_e64 s[0:1], v39, v43
	v_cmp_ge_u32_e64 s[6:7], v39, v43
	v_cmp_gt_u32_e64 s[4:5], v39, v43
	s_branch .LBB0_253

; __device__ __forceinline__ void phase_prep(const Args& a, PG8_LAS unsigned char* lds) {
;     ...
;     for (int unit = blockIdx.x; unit < 1024; unit += gridDim.x) {
;         const int hp = unit & 1, bn = unit >> 1, h = 2 * hp + half, item = bn * 4 + h; const size_t r0 = (size_t)bn * 64;
;         unsigned char* pi = a.ws + WS_PREP + (size_t)item * PREP_ITEM;
;         bf16_t* wp = (bf16_t*)(pi + PI_W); bf16_t* qgp = (bf16_t*)(pi + PI_QG); bf16_t* kdTp = (bf16_t*)(pi + PI_KD); bf16_t* uT = (bf16_t*)(pi + PI_UT); bf16_t* aqkp = (bf16_t*)(pi + PI_AQ);
;         const bf16_t* qbase = qb + r0 * 512 + h * 128; const bf16_t* kbase = kb + r0 * 512 + h * 128;
;         const bf16_t* kTb = kT + ((size_t)bn * 512 + h * 128) * 64; const bf16_t* vTb = vT + ((size_t)bn * 512 + h * 128) * 64;
;         bf16x8 ak[4], aq[4], bkf[2][4];
; #pragma unroll
;         for (int s = 0; s < 4; ++s) { ak[s] = *(const bf16x8*)(kbase + (size_t)(16 * lw + r) * 512 + 32 * s + 8 * q); aq[s] = *(const bf16x8*)(qbase + (size_t)(16 * lw + r) * 512 + 32 * s + 8 * q); }
; #pragma unroll
;         for (int tj = 0; tj < 2; ++tj)
; #pragma unroll
;             for (int s = 0; s < 4; ++s) bkf[tj][s] = *(const bf16x8*)(kbase + (size_t)(16 * tj + r) * 512 + 32 * s + 8 * q);
;         bf16x8 pv[2][2], pk[2][2];
;         if (role != 0) {
; #pragma unroll
;         for (int cc = 0; cc < 2; ++cc) { const int ct = 2 * lw + cc;
;             pv[cc][0] = *(const bf16x8*)(vTb + (size_t)(16 * ct + r) * 64 + 8 * q); pv[cc][1] = *(const bf16x8*)(vTb + (size_t)(16 * ct + r) * 64 + 32 + 8 * q);
;             pk[cc][0] = *(const bf16x8*)(kTb + (size_t)(16 * ct + r) * 64 + 8 * q); pk[cc][1] = *(const bf16x8*)(kTb + (size_t)(16 * ct + r) * 64 + 32 + 8 * q); } }
.LBB0_253:
	s_ashr_i32 s18, s38, 1
	s_lshl_b32 s14, s38, 1
	s_and_b32 s14, s14, 2
	s_ashr_i32 s19, s18, 31
	s_add_i32 s26, s14, s33
	s_lshl_b64 s[20:21], s[18:19], 15
	s_lshl_b64 s[24:25], s[18:19], 16
	v_readlane_b32 s14, v253, 43
	s_add_u32 s22, s14, s24
	v_readlane_b32 s14, v253, 44
	s_addc_u32 s23, s14, s25
	s_lshl_b32 s14, s26, 7
	s_lshl_b32 s27, s26, 8
	s_add_u32 s22, s22, s27
	s_addc_u32 s23, s23, 0
	v_readlane_b32 s39, v253, 45
	s_add_u32 s39, s39, s24
	v_readlane_b32 s40, v253, 46
	s_addc_u32 s40, s40, s25
	s_add_u32 vcc_lo, s39, s27
	s_addc_u32 vcc_hi, s40, 0
	v_mov_b32_e32 v107, v97
	v_lshl_add_u64 v[32:33], vcc, 0, v[106:107]
	v_lshl_add_u64 v[34:35], s[22:23], 0, v[106:107]
	v_lshl_add_u64 v[32:33], v[32:33], 0, v[96:97]
	v_lshl_add_u64 v[36:37], v[34:35], 0, v[96:97]
	s_lshl_b64 s[100:101], s[18:19], 8
	v_mov_b32_e32 v129, s101
	v_or_b32_e32 v128, s100, v98
	s_mov_b32 s100, s26
	s_mov_b32 s101, s15
	v_lshl_add_u64 v[128:129], v[128:129], 0, s[100:101]
	v_lshl_add_u64 v[230:231], v[128:129], 2, s[8:9]
	global_load_dword v234, v[230:231], off
	v_readlane_b32 s100, v253, 49
	v_readlane_b32 s101, v253, 50
	s_nop 1
	v_lshl_add_u64 v[232:233], v[128:129], 2, s[100:101]
	global_load_dword v111, v[232:233], off
	global_load_dwordx4 v[56:59], v[32:33], off
	global_load_dwordx4 v[48:51], v[32:33], off offset:64
	global_load_dwordx4 v[60:63], v[36:37], off
	global_load_dwordx4 v[52:55], v[36:37], off offset:64
	global_load_dwordx4 v[40:43], v[32:33], off offset:128
	s_nop 0
	global_load_dwordx4 v[32:35], v[32:33], off offset:192
	s_nop 0
	global_load_dwordx4 v[44:47], v[36:37], off offset:128
	s_nop 0
	global_load_dwordx4 v[36:39], v[36:37], off offset:192
	v_lshl_add_u64 v[64:65], vcc, 0, v[96:97]
	v_mov_b32_e32 v109, v97
	v_lshl_add_u64 v[126:127], v[64:65], 0, v[108:109]
	s_movk_i32 s22, 0x4000
	v_add_co_u32_e32 v64, vcc, s22, v126
	v_addc_co_u32_e32 v65, vcc, 0, v127, vcc
	s_nop 0
	s_lshl_b64 s[22:23], s[14:15], 6
	s_add_u32 s20, s22, s20
	s_addc_u32 s21, s23, s21
	s_lshl_b64 s[22:23], s[20:21], 1
	s_add_u32 s20, s10, s22
	s_addc_u32 s21, s11, s23
	v_readlane_b32 s14, v253, 47
	v_readlane_b32 s40, v253, 53
	s_add_u32 s22, s14, s22
	v_readlane_b32 s14, v253, 48
	v_readlane_b32 s41, v253, 54
	s_addc_u32 s23, s14, s23
	s_waitcnt vmcnt(8)
	s_andn2_b64 vcc, exec, s[40:41]
	s_cbranch_vccnz .LBB0_255
	v_mov_b32_e32 v115, v97
	v_lshl_add_u64 v[0:1], s[22:23], 0, v[114:115]
	v_lshl_add_u64 v[8:9], s[20:21], 0, v[114:115]
	v_lshl_add_u64 v[16:17], v[0:1], 0, v[96:97]
	v_lshl_add_u64 v[24:25], v[8:9], 0, v[96:97]
	global_load_dwordx4 v[0:3], v[16:17], off
	global_load_dwordx4 v[4:7], v[16:17], off offset:64
	global_load_dwordx4 v[8:11], v[24:25], off
	global_load_dwordx4 v[12:15], v[24:25], off offset:64
	global_load_dwordx4 v[20:23], v[16:17], off offset:2048
	global_load_dwordx4 v[28:31], v[16:17], off offset:2112
	s_nop 0
	global_load_dwordx4 v[16:19], v[24:25], off offset:2048
	s_nop 0
	global_load_dwordx4 v[24:27], v[24:25], off offset:2112

; #define MFMA16(a, b, c) __builtin_amdgcn_mfma_f32_16x16x32_bf16((a), (b), (c), 0, 0, 0)
; __device__ __forceinline__ void phase_prep(const Args& a, PG8_LAS unsigned char* lds) {
;     ...
;         {
; #pragma unroll
;             for (int tj = 0; tj < 4; ++tj) {
;                 f32x4 ckk = {0.f, 0.f, 0.f, 0.f}, cqk = {0.f, 0.f, 0.f, 0.f};
; #pragma unroll
;                 for (int s = 0; s < 4; ++s) { const bf16x8 bk = (tj < 2) ? bkf[tj & 1][s] : *(const bf16x8*)(kbase + (size_t)(16 * tj + r) * 512 + 32 * s + 8 * q); ckk = MFMA16(ak[s], bk, ckk); cqk = MFMA16(aq[s], bk, cqk); }
.Lpp_w1:
	ds_write_b128 v255, v[56:59]
	ds_write_b128 v255, v[48:51] offset:1024
	ds_write_b128 v255, v[40:43] offset:2048
	ds_write_b128 v255, v[32:35] offset:3072
	s_waitcnt lgkmcnt(0)
	s_barrier
	ds_read_b128 v[92:95], v254
	ds_read_b128 v[88:91], v254 offset:1024
	ds_read_b128 v[84:87], v254 offset:2048
	ds_read_b128 v[80:83], v254 offset:3072
	ds_read_b128 v[76:79], v254 offset:4096
	ds_read_b128 v[72:75], v254 offset:5120
	ds_read_b128 v[68:71], v254 offset:6144
	ds_read_b128 v[64:67], v254 offset:7168
	s_waitcnt lgkmcnt(0)
	v_mfma_f32_16x16x32_bf16 v[230:233], v[56:59], v[92:95], 0
	v_mfma_f32_16x16x32_bf16 v[92:95], v[60:63], v[92:95], 0
	v_readlane_b32 s40, v252, 5
	v_readlane_b32 s41, v252, 6
	v_mfma_f32_16x16x32_bf16 v[230:233], v[48:51], v[88:91], v[230:233]
	v_mfma_f32_16x16x32_bf16 v[88:91], v[52:55], v[88:91], v[92:95]
	v_mfma_f32_16x16x32_bf16 v[92:95], v[40:43], v[84:87], v[230:233]
	v_mfma_f32_16x16x32_bf16 v[230:233], v[44:47], v[84:87], v[88:91]
	s_nop 5
	ds_read_b32 v90, v137
	ds_read_b32 v89, v138 offset:256
	v_mov_b32_e32 v88, 0
	v_mov_b32_e32 v91, 0
	v_mfma_f32_16x16x32_bf16 v[84:87], v[32:35], v[80:83], v[92:95]
	v_mfma_f32_16x16x32_bf16 v[80:83], v[36:39], v[80:83], v[230:233]
	s_and_saveexec_b64 s[26:27], s[40:41]
	s_cbranch_execz .LBB0_261
	ds_read_b32 v91, v138
	s_waitcnt lgkmcnt(0)
	v_sub_f32_e32 v91, v91, v90
	v_mul_f32_e32 v91, 0x3fb8aa3b, v91
	v_exp_f32_e32 v91, v91

; #define PG8_LAS __attribute__((address_space(3)))
; #define MFMA16(a, b, c) __builtin_amdgcn_mfma_f32_16x16x32_bf16((a), (b), (c), 0, 0, 0)
; __device__ __forceinline__ bf16_t f2bf(float x) { return (bf16_t)(pk2(x, x) & 0xffffu); }
; __device__ __forceinline__ void phase_prep(const Args& a, PG8_LAS unsigned char* lds) {
;     ...
;             for (int tj = 0; tj < 4; ++tj) {
;                 f32x4 ckk = {0.f, 0.f, 0.f, 0.f}, cqk = {0.f, 0.f, 0.f, 0.f};
; #pragma unroll
;                 for (int s = 0; s < 4; ++s) { const bf16x8 bk = (tj < 2) ? bkf[tj & 1][s] : *(const bf16x8*)(kbase + (size_t)(16 * tj + r) * 512 + 32 * s + 8 * q); ckk = MFMA16(ak[s], bk, ckk); cqk = MFMA16(aq[s], bk, cqk); }
;                 const int j = 16 * tj + r; const float Gj = sG[j]; const int jpos = (j & 32) + perm32s(j & 31);
;                 f32x4 lv;
; #pragma unroll
;                 for (int e = 0; e < 4; ++e) { const int i = 16 * lw + 4 * q + e; const float Gi = sG[i], bi = sB[i];
;                     const float dec = (i >= j) ? __expf(Gi - Gj) : 0.f;
;                     lv[e] = (i > j) ? ckk[e] * bi * dec : 0.f;
;                     aqkp[i * 64 + jpos] = f2bf((i >= j) ? cqk[e] * dec : 0.f); }
;                 *(PG8_LAS f32x4*)(sL + j * 64 + 16 * lw + 4 * q) = lv;
.LBB0_275:
	s_or_b64 exec, exec, vcc
	s_waitcnt lgkmcnt(1)
	v_mul_f32_e32 v65, v70, v65
	v_mul_f32_e32 v65, v65, v76
	v_cndmask_b32_e64 v70, 0, v65, s[50:51]
	s_waitcnt lgkmcnt(0)
	v_mul_f32_e32 v65, v71, v66
	v_mul_f32_e32 v65, v65, v64
	v_mul_f32_e32 v64, v67, v64
	s_mov_b32 s14, 0x8000
	v_cndmask_b32_e64 v64, v64, 0, s[52:53]
	v_add_co_u32_e32 v78, vcc, s14, v126
	v_cvt_pk_bf16_f32 v64, v64, v64
	global_store_short v215, v64, s[26:27]
	s_nop 0
	v_addc_co_u32_e32 v79, vcc, 0, v127, vcc
	s_mov_b64 s[100:101], 0x4000
	v_lshl_add_u64 v[250:251], v[78:79], 0, s[100:101]
	v_cndmask_b32_e64 v71, 0, v65, s[56:57]
	ds_read_b128 v[64:67], v254 offset:8192
	v_mul_f32_e32 v69, v69, v75
	v_mul_f32_e32 v69, v69, v77
	ds_read_b128 v[74:77], v254 offset:9216
	ds_read_b128 v[234:237], v254 offset:10240
	ds_read_b128 v[238:241], v254 offset:11264
	ds_read_b128 v[242:245], v254 offset:12288
	ds_read_b128 v[246:249], v254 offset:13312
	v_mul_f32_e32 v68, v68, v73
	v_readlane_b32 s40, v252, 27
	v_mul_f32_e32 v68, v68, v80
	v_readlane_b32 s41, v252, 28
	v_cndmask_b32_e64 v69, v69, 0, s[36:37]
	s_nop 0
	v_cndmask_b32_e64 v68, 0, v68, s[40:41]
	ds_write_b128 v216, v[68:71] offset:1024
	s_waitcnt lgkmcnt(0)
	v_mfma_f32_16x16x32_bf16 v[68:71], v[56:59], v[64:67], 0
	v_mfma_f32_16x16x32_bf16 v[64:67], v[60:63], v[64:67], 0
	v_mfma_f32_16x16x32_bf16 v[68:71], v[48:51], v[74:77], v[68:71]
	v_mfma_f32_16x16x32_bf16 v[64:67], v[52:55], v[74:77], v[64:67]
	v_mfma_f32_16x16x32_bf16 v[68:71], v[40:43], v[234:237], v[68:71]
	v_mfma_f32_16x16x32_bf16 v[64:67], v[44:47], v[234:237], v[64:67]
	v_mfma_f32_16x16x32_bf16 v[68:71], v[32:35], v[238:241], v[68:71]
	v_mfma_f32_16x16x32_bf16 v[64:67], v[36:39], v[238:241], v[64:67]
	ds_read_b128 v[234:237], v254 offset:14336
	ds_read_b128 v[238:241], v254 offset:15360
	ds_read_b32 v74, v137 offset:128
	ds_read_b32 v73, v138 offset:256
	s_and_saveexec_b64 vcc, s[60:61]
	s_cbranch_execz .LBB0_277
	ds_read_b32 v72, v138
	s_waitcnt lgkmcnt(0)
	v_sub_f32_e32 v72, v72, v74
	v_mul_f32_e32 v72, 0x3fb8aa3b, v72
	v_exp_f32_e32 v72, v72

; #define PG8_LAS __attribute__((address_space(3)))
; #define MFMA16(a, b, c) __builtin_amdgcn_mfma_f32_16x16x32_bf16((a), (b), (c), 0, 0, 0)
; __device__ __forceinline__ bf16_t f2bf(float x) { return (bf16_t)(pk2(x, x) & 0xffffu); }
; __device__ __forceinline__ void phase_prep(const Args& a, PG8_LAS unsigned char* lds) {
;     ...
;             for (int tj = 0; tj < 4; ++tj) {
;                 f32x4 ckk = {0.f, 0.f, 0.f, 0.f}, cqk = {0.f, 0.f, 0.f, 0.f};
; #pragma unroll
;                 for (int s = 0; s < 4; ++s) { const bf16x8 bk = (tj < 2) ? bkf[tj & 1][s] : *(const bf16x8*)(kbase + (size_t)(16 * tj + r) * 512 + 32 * s + 8 * q); ckk = MFMA16(ak[s], bk, ckk); cqk = MFMA16(aq[s], bk, cqk); }
;                 const int j = 16 * tj + r; const float Gj = sG[j]; const int jpos = (j & 32) + perm32s(j & 31);
;                 f32x4 lv;
; #pragma unroll
;                 for (int e = 0; e < 4; ++e) { const int i = 16 * lw + 4 * q + e; const float Gi = sG[i], bi = sB[i];
;                     const float dec = (i >= j) ? __expf(Gi - Gj) : 0.f;
;                     lv[e] = (i > j) ? ckk[e] * bi * dec : 0.f;
;                     aqkp[i * 64 + jpos] = f2bf((i >= j) ? cqk[e] * dec : 0.f); }
;                 *(PG8_LAS f32x4*)(sL + j * 64 + 16 * lw + 4 * q) = lv;
.LBB0_283:
	s_or_b64 exec, exec, vcc
	s_waitcnt lgkmcnt(3)
	v_mul_f32_e32 v68, v68, v73
	s_waitcnt lgkmcnt(2)
	v_mul_f32_e32 v69, v69, v75
	s_waitcnt lgkmcnt(1)
	v_mul_f32_e32 v70, v70, v78
	s_waitcnt lgkmcnt(0)
	v_mul_f32_e32 v66, v71, v66
	v_mul_f32_e32 v68, v68, v72
	v_mul_f32_e32 v69, v69, v77
	v_mul_f32_e32 v70, v70, v76
	v_mul_f32_e32 v66, v66, v65
	v_mul_f32_e32 v65, v67, v65
	v_cndmask_b32_e64 v68, 0, v68, s[64:65]
	v_cndmask_b32_e64 v69, v69, 0, s[58:59]
	v_cndmask_b32_e64 v70, 0, v70, s[42:43]
	v_cndmask_b32_e64 v71, 0, v66, s[80:81]
	v_cndmask_b32_e64 v65, v65, 0, s[76:77]
	v_cvt_pk_bf16_f32 v65, v65, v65
	ds_write_b128 v221, v[68:71] offset:1024
	v_add_co_u32_e32 v70, vcc, s35, v126
	global_store_short v220, v65, s[26:27]
	s_nop 0
	v_addc_co_u32_e32 v71, vcc, 0, v127, vcc
	s_waitcnt lgkmcnt(0)
	v_mfma_f32_16x16x32_bf16 v[56:59], v[56:59], v[242:245], 0
	v_mfma_f32_16x16x32_bf16 v[60:63], v[60:63], v[242:245], 0
	v_mfma_f32_16x16x32_bf16 v[48:51], v[48:51], v[246:249], v[56:59]
	s_nop 3
	v_mfma_f32_16x16x32_bf16 v[52:55], v[52:55], v[246:249], v[60:63]
	v_mfma_f32_16x16x32_bf16 v[40:43], v[40:43], v[234:237], v[48:51]
	s_nop 2
	v_mfma_f32_16x16x32_bf16 v[44:47], v[44:47], v[234:237], v[52:55]
	v_mfma_f32_16x16x32_bf16 v[40:43], v[32:35], v[238:241], v[40:43]
	v_mfma_f32_16x16x32_bf16 v[32:35], v[36:39], v[238:241], v[44:47]
	ds_read_b32 v37, v137 offset:192
	ds_read_b32 v36, v138 offset:256
	s_and_saveexec_b64 vcc, s[84:85]
	s_cbranch_execz .LBB0_285
	ds_read_b32 v38, v138
	s_waitcnt lgkmcnt(0)
	v_sub_f32_e32 v38, v38, v37
	v_mul_f32_e32 v38, 0x3fb8aa3b, v38
	v_exp_f32_e32 v64, v38

; #define PG8_LAS __attribute__((address_space(3)))
; __device__ __forceinline__ void phase_scan(const Args& a, PG8_LAS unsigned char* lds, int sblk) {
;     const int tid = threadIdx.x, lane = tid & 63, wave = tid >> 6, q = lane >> 4, r = lane & 15;
;     const int bh = sblk >> 1, dvh = sblk & 1, b = bh >> 2, h = bh & 3;
;     bf16_t* of = (bf16_t*)(a.ws + WS_OF2); const float* glast = (const float*)(a.ws + WS_GL);
;     constexpr int L_W = 0, L_QG = 17408, L_KD = 34816, L_UT = 53248, L_AQ = 71680;
;     f32x4 S[8];
; #pragma unroll
;     for (int m = 0; m < 8; ++m) S[m] = (f32x4){0.f, 0.f, 0.f, 0.f};
;     u32x4 pre[9];
;     { const unsigned char* src = a.ws + WS_PREP + (size_t)((b * 32 + 0) * 4 + h) * PREP_ITEM;
; #pragma unroll
;       for (int i = 0; i < 9; ++i) pre[i] = __builtin_nontemporal_load((const u32x4*)(src + (size_t)(tid + 512 * i) * 16)); }
;     for (int n = 0; n < 32; ++n) {
; #pragma unroll
;         for (int i = 0; i < 9; ++i) { const int p = tid + 512 * i; int off;
;             if (i < 2) off = L_W + (p >> 4) * 272 + (p & 15) * 16;
;             else if (i < 4) { const int pp = p - 1024; off = L_QG + (pp >> 4) * 272 + (pp & 15) * 16; }
;             else if (i < 6) { const int pp = p - 2048; off = L_KD + (pp >> 3) * 144 + (pp & 7) * 16; }
;             else if (i < 8) { const int pp = p - 3072; off = L_UT + (pp >> 3) * 144 + (pp & 7) * 16; }
;             else { const int pp = p - 4096; off = L_AQ + (pp >> 3) * 144 + (pp & 7) * 16; }
;             *(PG8_LAS u32x4*)(lds + off) = pre[i]; }
;         __syncthreads();
;         if (n + 1 < 32) { const unsigned char* src = a.ws + WS_PREP + (size_t)((b * 32 + n + 1) * 4 + h) * PREP_ITEM;
; #pragma unroll
;             for (int i = 0; i < 9; ++i) pre[i] = __builtin_nontemporal_load((const u32x4*)(src + (size_t)(tid + 512 * i) * 16)); }
.LBB0_523:
	s_andn2_b64 vcc, exec, s[0:1]
	s_cbranch_vccnz .LBB0_531
	v_readlane_b32 s0, v253, 17
	s_bitcmp0_b32 s0, 4
	s_mov_b32 s5, 0
	s_cbranch_scc1 .LBB0_531
	s_lshr_b32 s52, s82, 4
	s_lshl_b32 s52, s52, 4
	s_and_b32 s53, s82, 7
	s_lshl_b32 s53, s53, 1
	s_or_b32 s52, s52, s53
	s_bfe_u32 s53, s82, 0x10003
	s_or_b32 s52, s52, s53
	s_lshr_b32 s4, s52, 3
	s_bfe_u32 s8, s52, 0x20001
	s_and_b32 s30, s52, 1
	s_add_u32 s12, s16, 0x16000000
	s_addc_u32 s13, s17, 0
	s_lshl_b32 s0, s4, 7
	s_or_b32 s20, s0, s8
	s_mul_i32 s0, s20, 0x12000
	s_add_u32 s88, s12, s0
	s_addc_u32 s89, s13, 0
	v_mov_b32_e32 v95, 0
	s_waitcnt vmcnt(0)
	v_readfirstlane_b32 s56, v152
	s_mov_b32 s57, 0
	s_mov_b32 s86, 0
	s_lshr_b32 s56, s56, 6
	s_cmp_lt_u32 s56, 4
	s_cbranch_scc1 .Lsc_consumer
	s_cmp_lt_u32 s56, 6
	s_mov_b32 s69, 0x1c72
	s_cselect_b32 s69, 0xf10, s69
	s_cselect_b32 s70, 17, 9
	s_cselect_b32 s71, 15, 7
	s_movk_i32 s72, 0x80
	s_cselect_b32 s72, 0x100, s72
	s_mov_b32 s75, 0
	s_cmp_eq_u32 s56, 4
	s_cbranch_scc1 .Lsc_ld_w4
	s_cmp_eq_u32 s56, 5
	s_cbranch_scc1 .Lsc_ld_w5
	s_cmp_eq_u32 s56, 6
	s_cbranch_scc1 .Lsc_ld_w6
	s_mov_b32 s73, 0x10000
	s_mov_b32 s90, 0
	s_lshl_b32 s74, s30, 13
	s_add_i32 s74, s74, 0xc000
	s_mov_b32 s75, 0xfffffdc0
	s_mov_b32 s60, 71680
	s_mov_b32 s62, 217344
	s_mul_i32 s61, s30, 0x2400
	s_add_i32 s61, s61, 44032
	s_xor_b32 s63, s61, 106496
	s_branch .Lsc_ld_tab
.Lsc_ld_w4:
	s_mov_b32 s73, 0x0
	s_mov_b32 s90, 0x2000
	s_mov_b32 s74, 0x0
	s_mov_b32 s60, 0
	s_mov_b32 s62, 80896
	s_mov_b32 s61, 0
	s_mov_b32 s63, 80896
	s_branch .Lsc_ld_tab
.Lsc_ld_w5:
	s_mov_b32 s73, 0x4000
	s_mov_b32 s90, 0x2000
	s_mov_b32 s74, 0x4000
	s_mov_b32 s60, 17408
	s_mov_b32 s62, 115712
	s_mov_b32 s61, 17408
	s_mov_b32 s63, 115712
	s_branch .Lsc_ld_tab
.Lsc_ld_w6:
	s_mov_b32 s73, 0x8000
	s_mov_b32 s90, 0x2000
	s_mov_b32 s74, 0x8000
	s_mov_b32 s60, 34816
	s_mov_b32 s62, 166144
	s_mov_b32 s61, 34816
	s_mov_b32 s63, 166144
